# attention steady loops unrolled x2 (K fragment sets alternate, no per-iteration copies); FOX bias rows pre-divided by the score scale when the table is built
# speedup vs baseline: 1.0256x; 1.0107x over previous
.Ldf_nr1a:
	v_mfma_f32_32x32x16_bf16 v[50:65], v[166:169], v[106:109], v[50:65]
	v_mfma_f32_32x32x16_bf16 v[34:49], v[158:161], v[106:109], v[34:49]
	v_mfma_f32_32x32x16_bf16 v[50:65], v[162:165], v[110:113], v[50:65]
	v_mfma_f32_32x32x16_bf16 v[34:49], v[154:157], v[110:113], v[34:49]
	s_and_b64 vcc, exec, s[4:5]
	s_cbranch_vccnz .Ldf_exit
	s_add_i32 s15, s15, -1
	v_lshl_add_u64 v[180:181], v[180:181], 0, s[84:85]
	s_cmp_le_i32 s15, s73
	s_cselect_b64 s[4:5], -1, 0
	s_add_i32 s100, s15, -1
	s_cmp_le_i32 s15, s73
	s_cselect_b32 s76, s15, s100
	s_lshl_b64 s[16:17], s[76:77], 12
	s_waitcnt vmcnt(0)
	global_load_dwordx4 v[166:169], v[180:181], off offset:-2048
	global_load_dwordx4 v[162:165], v[180:181], off offset:-1024
	global_load_dwordx4 v[158:161], v[180:181], off
	global_load_dwordx4 v[154:157], v[180:181], off offset:1024
	v_lshl_add_u64 v[220:221], v[178:179], 0, s[16:17]
	global_load_dwordx4 v[170:173], v[220:221], off
	global_load_dwordx4 v[174:177], v[220:221], off offset:1024
	s_branch .Ldf_iterb
.Ldf_iterb:
	v_mfma_f32_32x32x16_bf16 v[2:17], v[146:149], v[130:133], v[114:129]
	v_mfma_f32_32x32x16_bf16 v[18:33], v[146:149], v[138:141], v[114:129]
	v_mfma_f32_32x32x16_bf16 v[2:17], v[150:153], v[134:137], v[2:17]
	v_mfma_f32_32x32x16_bf16 v[18:33], v[150:153], v[142:145], v[18:33]
	v_mul_f32_e64 v198, -v200, v205
	v_fmamk_f32 v199, v200, 0xc2000000, v198
	v_add_f32_e32 v205, 0x42000000, v205
	s_nop 7
	v_max3_f32 v206, v2, v3, v4
	v_max3_f32 v207, v5, v6, v7
	v_max3_f32 v208, v8, v9, v10
	v_max3_f32 v209, v11, v12, v13
	v_max3_f32 v206, v206, v14, v15
	v_max3_f32 v207, v207, v16, v17
	v_max3_f32 v206, v206, v207, v208
	v_max_f32_e32 v206, v206, v209
	v_fma_f32 v206, v206, s98, v198
	v_mov_b32_e32 v207, v206
	s_nop 1
	v_permlane32_swap_b32_e32 v206, v207
	v_max3_f32 v194, v188, v206, v207
	v_sub_f32_e32 v208, v188, v194
	v_sub_f32_e32 v196, v198, v194
	v_exp_f32_e32 v190, v208
	v_fma_f32 v2, v2, s98, v196
	v_fma_f32 v3, v3, s98, v196
	v_fma_f32 v4, v4, s98, v196
	v_fma_f32 v5, v5, s98, v196
	v_fma_f32 v6, v6, s98, v196
	v_fma_f32 v7, v7, s98, v196
	v_fma_f32 v8, v8, s98, v196
	v_fma_f32 v9, v9, s98, v196
	v_fma_f32 v10, v10, s98, v196
	v_fma_f32 v11, v11, s98, v196
	v_fma_f32 v12, v12, s98, v196
	v_fma_f32 v13, v13, s98, v196
	v_fma_f32 v14, v14, s98, v196
	v_fma_f32 v15, v15, s98, v196
	v_fma_f32 v16, v16, s98, v196
	v_fma_f32 v17, v17, s98, v196
	v_exp_f32_e32 v2, v2
	v_exp_f32_e32 v3, v3
	v_exp_f32_e32 v4, v4
	v_exp_f32_e32 v5, v5
	v_exp_f32_e32 v6, v6
	v_exp_f32_e32 v7, v7
	v_exp_f32_e32 v8, v8
	v_exp_f32_e32 v9, v9
	v_exp_f32_e32 v10, v10
	v_exp_f32_e32 v11, v11
	v_exp_f32_e32 v12, v12
	v_exp_f32_e32 v13, v13
	v_exp_f32_e32 v14, v14
	v_exp_f32_e32 v15, v15
	v_exp_f32_e32 v16, v16
	v_exp_f32_e32 v17, v17
	v_cmp_lt_f32_e32 vcc, v188, v194
	v_mov_b32_e32 v188, v194
	v_cvt_pk_bf16_f32 v98, v2, v3
	v_cvt_pk_bf16_f32 v99, v4, v5
	v_cvt_pk_bf16_f32 v100, v6, v7
	v_cvt_pk_bf16_f32 v101, v8, v9
	v_cvt_pk_bf16_f32 v102, v10, v11
	v_cvt_pk_bf16_f32 v103, v12, v13
	v_cvt_pk_bf16_f32 v104, v14, v15
	v_cvt_pk_bf16_f32 v105, v16, v17
	v_add_f32_e32 v206, v2, v3
	v_add_f32_e32 v207, v4, v5
	v_add_f32_e32 v208, v6, v7
	v_add_f32_e32 v209, v8, v9
	v_add_f32_e32 v206, v206, v10
	v_add_f32_e32 v207, v207, v11
	v_add_f32_e32 v208, v208, v12
	v_add_f32_e32 v209, v209, v13
	v_add_f32_e32 v206, v206, v14
	v_add_f32_e32 v207, v207, v15
	v_add_f32_e32 v208, v208, v16
	v_add_f32_e32 v209, v209, v17
	v_add_f32_e32 v206, v206, v207
	v_add_f32_e32 v208, v208, v209
	v_add_f32_e32 v206, v206, v208
	v_fmac_f32_e32 v206, v182, v190
	v_mov_b32_e32 v182, v206
	s_cbranch_vccz .Ldf_nr0b
	v_pk_mul_f32 v[82:83], v[82:83], v[190:191] op_sel_hi:[1,0]
	v_pk_mul_f32 v[84:85], v[84:85], v[190:191] op_sel_hi:[1,0]
	v_pk_mul_f32 v[86:87], v[86:87], v[190:191] op_sel_hi:[1,0]
	v_pk_mul_f32 v[88:89], v[88:89], v[190:191] op_sel_hi:[1,0]
	v_pk_mul_f32 v[90:91], v[90:91], v[190:191] op_sel_hi:[1,0]
	v_pk_mul_f32 v[92:93], v[92:93], v[190:191] op_sel_hi:[1,0]
	v_pk_mul_f32 v[94:95], v[94:95], v[190:191] op_sel_hi:[1,0]
	v_pk_mul_f32 v[96:97], v[96:97], v[190:191] op_sel_hi:[1,0]
	v_pk_mul_f32 v[66:67], v[66:67], v[190:191] op_sel_hi:[1,0]
	v_pk_mul_f32 v[68:69], v[68:69], v[190:191] op_sel_hi:[1,0]
	v_pk_mul_f32 v[70:71], v[70:71], v[190:191] op_sel_hi:[1,0]
	v_pk_mul_f32 v[72:73], v[72:73], v[190:191] op_sel_hi:[1,0]
	v_pk_mul_f32 v[74:75], v[74:75], v[190:191] op_sel_hi:[1,0]
	v_pk_mul_f32 v[76:77], v[76:77], v[190:191] op_sel_hi:[1,0]
	v_pk_mul_f32 v[78:79], v[78:79], v[190:191] op_sel_hi:[1,0]
	v_pk_mul_f32 v[80:81], v[80:81], v[190:191] op_sel_hi:[1,0]
	s_nop 1

.Ldf_nr1b:
	v_mfma_f32_32x32x16_bf16 v[50:65], v[166:169], v[106:109], v[50:65]
	v_mfma_f32_32x32x16_bf16 v[34:49], v[158:161], v[106:109], v[34:49]
	v_mfma_f32_32x32x16_bf16 v[50:65], v[162:165], v[110:113], v[50:65]
	v_mfma_f32_32x32x16_bf16 v[34:49], v[154:157], v[110:113], v[34:49]
	s_and_b64 vcc, exec, s[4:5]
	s_cbranch_vccnz .Ldf_exit
	s_add_i32 s15, s15, -1
	v_lshl_add_u64 v[180:181], v[180:181], 0, s[84:85]
	s_cmp_le_i32 s15, s73
	s_cselect_b64 s[4:5], -1, 0
	s_add_i32 s100, s15, -1
	s_cmp_le_i32 s15, s73
	s_cselect_b32 s76, s15, s100
	s_lshl_b64 s[16:17], s[76:77], 12
	s_waitcnt vmcnt(0)
	global_load_dwordx4 v[166:169], v[180:181], off offset:-2048
	global_load_dwordx4 v[162:165], v[180:181], off offset:-1024
	global_load_dwordx4 v[158:161], v[180:181], off
	global_load_dwordx4 v[154:157], v[180:181], off offset:1024
	v_lshl_add_u64 v[220:221], v[178:179], 0, s[16:17]
	global_load_dwordx4 v[146:149], v[220:221], off
	global_load_dwordx4 v[150:153], v[220:221], off offset:1024
	s_branch .Ldf_itera

.LBB0_415:
	s_or_b64 exec, exec, s[16:17]
	v_lshlrev_b32_e32 v3, 2, v247
	v_add_u32_e32 v2, -4, v3
	ds_bpermute_b32 v2, v2, v5
	v_cmp_gt_i32_e64 s[4:5], 1, v247
	v_add_u32_e32 v4, -8, v3
	s_waitcnt lgkmcnt(0)
	v_add_f32_e32 v2, v5, v2
	v_cndmask_b32_e64 v2, v2, v5, s[4:5]
	ds_bpermute_b32 v4, v4, v2
	v_cmp_gt_i32_e64 s[4:5], 2, v247
	s_waitcnt lgkmcnt(0)
	v_add_f32_e32 v4, v2, v4
	v_cndmask_b32_e64 v2, v4, v2, s[4:5]
	v_add_u32_e32 v4, -16, v3
	ds_bpermute_b32 v4, v4, v2
	v_cmp_gt_i32_e64 s[4:5], 4, v247
	s_waitcnt lgkmcnt(0)
	v_add_f32_e32 v4, v2, v4
	v_cndmask_b32_e64 v2, v4, v2, s[4:5]
	v_subrev_u32_e32 v4, 32, v3
	ds_bpermute_b32 v4, v4, v2
	v_cmp_gt_i32_e64 s[4:5], 8, v247
	s_waitcnt lgkmcnt(0)
	v_add_f32_e32 v4, v2, v4
	v_cndmask_b32_e64 v2, v4, v2, s[4:5]
	v_subrev_u32_e32 v4, 64, v3
	ds_bpermute_b32 v4, v4, v2
	v_cmp_gt_i32_e64 s[4:5], 16, v247
	v_add_u32_e32 v3, 0xffffff80, v3
	s_waitcnt lgkmcnt(0)
	v_add_f32_e32 v4, v2, v4
	v_cndmask_b32_e64 v2, v4, v2, s[4:5]
	ds_bpermute_b32 v3, v3, v2
	s_and_saveexec_b64 s[4:5], vcc
	s_cbranch_execz .LBB0_418
	s_waitcnt lgkmcnt(0)
	v_add_f32_e32 v3, v2, v3
	v_cmp_gt_i32_e32 vcc, 32, v247
	s_mov_b32 s3, 0
	s_nop 0
	v_cndmask_b32_e32 v2, v3, v2, vcc
	v_sub_f32_e32 v2, v2, v5
	v_mov_b32_e32 v3, v2
	v_mov_b32_e32 v8, s86
	v_mov_b32_e32 v9, 0xc1000000
	v_cmp_gt_i32_e32 vcc, s71, v247
	s_nop 1
	v_cndmask_b32_e32 v8, v8, v9, vcc
.LBB0_417:
	v_add_u32_e32 v6, s3, v0
	ds_read2_b32 v[4:5], v6 offset1:1
	s_add_i32 s3, s3, 64
	s_cmpk_lg_i32 s3, 0x80
	s_waitcnt lgkmcnt(0)
	v_pk_add_f32 v[4:5], v[2:3], v[4:5]
	s_nop 0
	v_pk_mul_f32 v[4:5], v[4:5], v[8:9] op_sel_hi:[1,0]
	ds_write2_b32 v6, v4, v5 offset1:1
	ds_read2_b32 v[4:5], v6 offset0:2 offset1:3
	s_waitcnt lgkmcnt(0)
	v_pk_add_f32 v[4:5], v[2:3], v[4:5]
	s_nop 0
	v_pk_mul_f32 v[4:5], v[4:5], v[8:9] op_sel_hi:[1,0]
	ds_write2_b32 v6, v4, v5 offset0:2 offset1:3
	ds_read2_b32 v[4:5], v6 offset0:4 offset1:5
	s_waitcnt lgkmcnt(0)
	v_pk_add_f32 v[4:5], v[2:3], v[4:5]
	s_nop 0
	v_pk_mul_f32 v[4:5], v[4:5], v[8:9] op_sel_hi:[1,0]
	ds_write2_b32 v6, v4, v5 offset0:4 offset1:5
	ds_read2_b32 v[4:5], v6 offset0:6 offset1:7
	s_waitcnt lgkmcnt(0)
	v_pk_add_f32 v[4:5], v[2:3], v[4:5]
	s_nop 0
	v_pk_mul_f32 v[4:5], v[4:5], v[8:9] op_sel_hi:[1,0]
	ds_write2_b32 v6, v4, v5 offset0:6 offset1:7
	ds_read2_b32 v[4:5], v6 offset0:8 offset1:9
	s_waitcnt lgkmcnt(0)
	v_pk_add_f32 v[4:5], v[2:3], v[4:5]
	s_nop 0
	v_pk_mul_f32 v[4:5], v[4:5], v[8:9] op_sel_hi:[1,0]
	ds_write2_b32 v6, v4, v5 offset0:8 offset1:9
	ds_read2_b32 v[4:5], v6 offset0:10 offset1:11
	s_waitcnt lgkmcnt(0)
	v_pk_add_f32 v[4:5], v[2:3], v[4:5]
	s_nop 0
	v_pk_mul_f32 v[4:5], v[4:5], v[8:9] op_sel_hi:[1,0]
	ds_write2_b32 v6, v4, v5 offset0:10 offset1:11
	ds_read2_b32 v[4:5], v6 offset0:12 offset1:13
	s_waitcnt lgkmcnt(0)
	v_pk_add_f32 v[4:5], v[2:3], v[4:5]
	s_nop 0
	v_pk_mul_f32 v[4:5], v[4:5], v[8:9] op_sel_hi:[1,0]
	ds_write2_b32 v6, v4, v5 offset0:12 offset1:13
	ds_read2_b32 v[4:5], v6 offset0:14 offset1:15
	s_waitcnt lgkmcnt(0)
	v_pk_add_f32 v[4:5], v[2:3], v[4:5]
	s_nop 0
	v_pk_mul_f32 v[4:5], v[4:5], v[8:9] op_sel_hi:[1,0]
	ds_write2_b32 v6, v4, v5 offset0:14 offset1:15
	s_cbranch_scc1 .LBB0_417

.Lfx_itera:
	s_waitcnt lgkmcnt(0)
	v_mfma_f32_32x32x16_bf16 v[2:17], v[206:209], v[130:133], v[114:129]
	v_mfma_f32_32x32x16_bf16 v[18:33], v[206:209], v[146:149], v[114:129]
	v_mfma_f32_32x32x16_bf16 v[2:17], v[202:205], v[134:137], v[2:17]
	v_mfma_f32_32x32x16_bf16 v[18:33], v[202:205], v[150:153], v[18:33]
	v_mfma_f32_32x32x16_bf16 v[2:17], v[198:201], v[138:141], v[2:17]
	v_mfma_f32_32x32x16_bf16 v[18:33], v[198:201], v[154:157], v[18:33]
	v_mfma_f32_32x32x16_bf16 v[2:17], v[194:197], v[142:145], v[2:17]
	v_mfma_f32_32x32x16_bf16 v[18:33], v[194:197], v[158:161], v[18:33]
	s_nop 10
	v_max3_f32 v230, v2, v3, v4
	v_max3_f32 v231, v5, v6, v7
	v_max3_f32 v232, v8, v9, v10
	v_max3_f32 v233, v11, v12, v13
	v_max3_f32 v230, v230, v14, v15
	v_max3_f32 v231, v231, v16, v17
	v_max3_f32 v230, v230, v231, v232
	v_max_f32_e32 v230, v230, v233
	v_mul_f32_e32 v230, s98, v230
	v_mov_b32_e32 v231, v230
	s_nop 1
	v_permlane32_swap_b32_e32 v230, v231
	v_max3_f32 v220, v224, v230, v231
	v_sub_f32_e32 v232, v224, v220
	v_exp_f32_e32 v226, v232
	v_fma_f32 v2, v2, s98, -v220
	v_fma_f32 v3, v3, s98, -v220
	v_fma_f32 v4, v4, s98, -v220
	v_fma_f32 v5, v5, s98, -v220
	v_fma_f32 v6, v6, s98, -v220
	v_fma_f32 v7, v7, s98, -v220
	v_fma_f32 v8, v8, s98, -v220
	v_fma_f32 v9, v9, s98, -v220
	v_fma_f32 v10, v10, s98, -v220
	v_fma_f32 v11, v11, s98, -v220
	v_fma_f32 v12, v12, s98, -v220
	v_fma_f32 v13, v13, s98, -v220
	v_fma_f32 v14, v14, s98, -v220
	v_fma_f32 v15, v15, s98, -v220
	v_fma_f32 v16, v16, s98, -v220
	v_fma_f32 v17, v17, s98, -v220
	v_exp_f32_e32 v2, v2
	v_exp_f32_e32 v3, v3
	v_exp_f32_e32 v4, v4
	v_exp_f32_e32 v5, v5
	v_exp_f32_e32 v6, v6
	v_exp_f32_e32 v7, v7
	v_exp_f32_e32 v8, v8
	v_exp_f32_e32 v9, v9
	v_exp_f32_e32 v10, v10
	v_exp_f32_e32 v11, v11
	v_exp_f32_e32 v12, v12
	v_exp_f32_e32 v13, v13
	v_exp_f32_e32 v14, v14
	v_exp_f32_e32 v15, v15
	v_exp_f32_e32 v16, v16
	v_exp_f32_e32 v17, v17
	v_cmp_lt_f32_e32 vcc, v224, v220
	v_mov_b32_e32 v224, v220
	v_cvt_pk_bf16_f32 v98, v2, v3
	v_cvt_pk_bf16_f32 v99, v4, v5
	v_cvt_pk_bf16_f32 v100, v6, v7
	v_cvt_pk_bf16_f32 v101, v8, v9
	v_cvt_pk_bf16_f32 v102, v10, v11
	v_cvt_pk_bf16_f32 v103, v12, v13
	v_cvt_pk_bf16_f32 v104, v14, v15
	v_cvt_pk_bf16_f32 v105, v16, v17
	v_add_f32_e32 v230, v2, v3
	v_add_f32_e32 v231, v4, v5
	v_add_f32_e32 v232, v6, v7
	v_add_f32_e32 v233, v8, v9
	v_add_f32_e32 v230, v230, v10
	v_add_f32_e32 v231, v231, v11
	v_add_f32_e32 v232, v232, v12
	v_add_f32_e32 v233, v233, v13
	v_add_f32_e32 v230, v230, v14
	v_add_f32_e32 v231, v231, v15
	v_add_f32_e32 v232, v232, v16
	v_add_f32_e32 v233, v233, v17
	v_add_f32_e32 v230, v230, v231
	v_add_f32_e32 v232, v232, v233
	v_add_f32_e32 v230, v230, v232
	v_fmac_f32_e32 v230, v218, v226
	v_mov_b32_e32 v218, v230
	s_cbranch_vccz .Lfx_nr0a
	v_pk_mul_f32 v[82:83], v[82:83], v[226:227] op_sel_hi:[1,0]
	v_pk_mul_f32 v[84:85], v[84:85], v[226:227] op_sel_hi:[1,0]
	v_pk_mul_f32 v[86:87], v[86:87], v[226:227] op_sel_hi:[1,0]
	v_pk_mul_f32 v[88:89], v[88:89], v[226:227] op_sel_hi:[1,0]
	v_pk_mul_f32 v[90:91], v[90:91], v[226:227] op_sel_hi:[1,0]
	v_pk_mul_f32 v[92:93], v[92:93], v[226:227] op_sel_hi:[1,0]
	v_pk_mul_f32 v[94:95], v[94:95], v[226:227] op_sel_hi:[1,0]
	v_pk_mul_f32 v[96:97], v[96:97], v[226:227] op_sel_hi:[1,0]
	v_pk_mul_f32 v[66:67], v[66:67], v[226:227] op_sel_hi:[1,0]
	v_pk_mul_f32 v[68:69], v[68:69], v[226:227] op_sel_hi:[1,0]
	v_pk_mul_f32 v[70:71], v[70:71], v[226:227] op_sel_hi:[1,0]
	v_pk_mul_f32 v[72:73], v[72:73], v[226:227] op_sel_hi:[1,0]
	v_pk_mul_f32 v[74:75], v[74:75], v[226:227] op_sel_hi:[1,0]
	v_pk_mul_f32 v[76:77], v[76:77], v[226:227] op_sel_hi:[1,0]
	v_pk_mul_f32 v[78:79], v[78:79], v[226:227] op_sel_hi:[1,0]
	v_pk_mul_f32 v[80:81], v[80:81], v[226:227] op_sel_hi:[1,0]
	s_nop 1

.Lfx_nr1a:
	v_mfma_f32_32x32x16_bf16 v[50:65], v[190:193], v[106:109], v[50:65]
	v_mfma_f32_32x32x16_bf16 v[34:49], v[182:185], v[106:109], v[34:49]
	v_mfma_f32_32x32x16_bf16 v[50:65], v[186:189], v[110:113], v[50:65]
	v_mfma_f32_32x32x16_bf16 v[34:49], v[178:181], v[110:113], v[34:49]
	s_and_b64 vcc, exec, s[4:5]
	s_cbranch_vccnz .Lfx_exit
	s_add_i32 s14, s14, -1
	v_add_u32_e32 v0, 0xffffff7c, v0
	v_lshl_add_u64 v[216:217], v[216:217], 0, s[84:85]
	s_cmp_le_i32 s14, s73
	s_cselect_b64 s[4:5], -1, 0
	s_add_i32 s100, s14, -1
	s_cmp_le_i32 s14, s73
	s_cselect_b32 s76, s14, s100
	s_lshl_b64 s[16:17], s[76:77], 12
	ds_read2_b32 v[114:115], v0 offset1:1
	ds_read2_b32 v[116:117], v0 offset0:2 offset1:3
	ds_read2_b32 v[118:119], v0 offset0:8 offset1:9
	ds_read2_b32 v[120:121], v0 offset0:10 offset1:11
	ds_read2_b32 v[122:123], v0 offset0:16 offset1:17
	ds_read2_b32 v[124:125], v0 offset0:18 offset1:19
	ds_read2_b32 v[126:127], v0 offset0:24 offset1:25
	ds_read2_b32 v[128:129], v0 offset0:26 offset1:27
	s_waitcnt vmcnt(0)
	global_load_dwordx4 v[190:193], v[216:217], off offset:-2048
	global_load_dwordx4 v[186:189], v[216:217], off offset:-1024
	global_load_dwordx4 v[182:185], v[216:217], off
	global_load_dwordx4 v[178:181], v[216:217], off offset:1024
	v_lshl_add_u64 v[234:235], v[214:215], 0, s[16:17]
	global_load_dwordx4 v[206:209], v[234:235], off
	global_load_dwordx4 v[202:205], v[234:235], off offset:1024
	global_load_dwordx4 v[198:201], v[234:235], off offset:2048
	global_load_dwordx4 v[194:197], v[234:235], off offset:3072
	s_branch .Lfx_iterb
.Lfx_iterb:
	s_waitcnt lgkmcnt(0)
	v_mfma_f32_32x32x16_bf16 v[2:17], v[174:177], v[130:133], v[114:129]
	v_mfma_f32_32x32x16_bf16 v[18:33], v[174:177], v[146:149], v[114:129]
	v_mfma_f32_32x32x16_bf16 v[2:17], v[170:173], v[134:137], v[2:17]
	v_mfma_f32_32x32x16_bf16 v[18:33], v[170:173], v[150:153], v[18:33]
	v_mfma_f32_32x32x16_bf16 v[2:17], v[166:169], v[138:141], v[2:17]
	v_mfma_f32_32x32x16_bf16 v[18:33], v[166:169], v[154:157], v[18:33]
	v_mfma_f32_32x32x16_bf16 v[2:17], v[162:165], v[142:145], v[2:17]
	v_mfma_f32_32x32x16_bf16 v[18:33], v[162:165], v[158:161], v[18:33]
	s_nop 10
	v_max3_f32 v230, v2, v3, v4
	v_max3_f32 v231, v5, v6, v7
	v_max3_f32 v232, v8, v9, v10
	v_max3_f32 v233, v11, v12, v13
	v_max3_f32 v230, v230, v14, v15
	v_max3_f32 v231, v231, v16, v17
	v_max3_f32 v230, v230, v231, v232
	v_max_f32_e32 v230, v230, v233
	v_mul_f32_e32 v230, s98, v230
	v_mov_b32_e32 v231, v230
	s_nop 1
	v_permlane32_swap_b32_e32 v230, v231
	v_max3_f32 v220, v224, v230, v231
	v_sub_f32_e32 v232, v224, v220
	v_exp_f32_e32 v226, v232
	v_fma_f32 v2, v2, s98, -v220
	v_fma_f32 v3, v3, s98, -v220
	v_fma_f32 v4, v4, s98, -v220
	v_fma_f32 v5, v5, s98, -v220
	v_fma_f32 v6, v6, s98, -v220
	v_fma_f32 v7, v7, s98, -v220
	v_fma_f32 v8, v8, s98, -v220
	v_fma_f32 v9, v9, s98, -v220
	v_fma_f32 v10, v10, s98, -v220
	v_fma_f32 v11, v11, s98, -v220
	v_fma_f32 v12, v12, s98, -v220
	v_fma_f32 v13, v13, s98, -v220
	v_fma_f32 v14, v14, s98, -v220
	v_fma_f32 v15, v15, s98, -v220
	v_fma_f32 v16, v16, s98, -v220
	v_fma_f32 v17, v17, s98, -v220
	v_exp_f32_e32 v2, v2
	v_exp_f32_e32 v3, v3
	v_exp_f32_e32 v4, v4
	v_exp_f32_e32 v5, v5
	v_exp_f32_e32 v6, v6
	v_exp_f32_e32 v7, v7
	v_exp_f32_e32 v8, v8
	v_exp_f32_e32 v9, v9
	v_exp_f32_e32 v10, v10
	v_exp_f32_e32 v11, v11
	v_exp_f32_e32 v12, v12
	v_exp_f32_e32 v13, v13
	v_exp_f32_e32 v14, v14
	v_exp_f32_e32 v15, v15
	v_exp_f32_e32 v16, v16
	v_exp_f32_e32 v17, v17
	v_cmp_lt_f32_e32 vcc, v224, v220
	v_mov_b32_e32 v224, v220
	v_cvt_pk_bf16_f32 v98, v2, v3
	v_cvt_pk_bf16_f32 v99, v4, v5
	v_cvt_pk_bf16_f32 v100, v6, v7
	v_cvt_pk_bf16_f32 v101, v8, v9
	v_cvt_pk_bf16_f32 v102, v10, v11
	v_cvt_pk_bf16_f32 v103, v12, v13
	v_cvt_pk_bf16_f32 v104, v14, v15
	v_cvt_pk_bf16_f32 v105, v16, v17
	v_add_f32_e32 v230, v2, v3
	v_add_f32_e32 v231, v4, v5
	v_add_f32_e32 v232, v6, v7
	v_add_f32_e32 v233, v8, v9
	v_add_f32_e32 v230, v230, v10
	v_add_f32_e32 v231, v231, v11
	v_add_f32_e32 v232, v232, v12
	v_add_f32_e32 v233, v233, v13
	v_add_f32_e32 v230, v230, v14
	v_add_f32_e32 v231, v231, v15
	v_add_f32_e32 v232, v232, v16
	v_add_f32_e32 v233, v233, v17
	v_add_f32_e32 v230, v230, v231
	v_add_f32_e32 v232, v232, v233
	v_add_f32_e32 v230, v230, v232
	v_fmac_f32_e32 v230, v218, v226
	v_mov_b32_e32 v218, v230
	s_cbranch_vccz .Lfx_nr0b
	v_pk_mul_f32 v[82:83], v[82:83], v[226:227] op_sel_hi:[1,0]
	v_pk_mul_f32 v[84:85], v[84:85], v[226:227] op_sel_hi:[1,0]
	v_pk_mul_f32 v[86:87], v[86:87], v[226:227] op_sel_hi:[1,0]
	v_pk_mul_f32 v[88:89], v[88:89], v[226:227] op_sel_hi:[1,0]
	v_pk_mul_f32 v[90:91], v[90:91], v[226:227] op_sel_hi:[1,0]
	v_pk_mul_f32 v[92:93], v[92:93], v[226:227] op_sel_hi:[1,0]
	v_pk_mul_f32 v[94:95], v[94:95], v[226:227] op_sel_hi:[1,0]
	v_pk_mul_f32 v[96:97], v[96:97], v[226:227] op_sel_hi:[1,0]
	v_pk_mul_f32 v[66:67], v[66:67], v[226:227] op_sel_hi:[1,0]
	v_pk_mul_f32 v[68:69], v[68:69], v[226:227] op_sel_hi:[1,0]
	v_pk_mul_f32 v[70:71], v[70:71], v[226:227] op_sel_hi:[1,0]
	v_pk_mul_f32 v[72:73], v[72:73], v[226:227] op_sel_hi:[1,0]
	v_pk_mul_f32 v[74:75], v[74:75], v[226:227] op_sel_hi:[1,0]
	v_pk_mul_f32 v[76:77], v[76:77], v[226:227] op_sel_hi:[1,0]
	v_pk_mul_f32 v[78:79], v[78:79], v[226:227] op_sel_hi:[1,0]
	v_pk_mul_f32 v[80:81], v[80:81], v[226:227] op_sel_hi:[1,0]
	s_nop 1

.Lfx_nr1b:
	v_mfma_f32_32x32x16_bf16 v[50:65], v[190:193], v[106:109], v[50:65]
	v_mfma_f32_32x32x16_bf16 v[34:49], v[182:185], v[106:109], v[34:49]
	v_mfma_f32_32x32x16_bf16 v[50:65], v[186:189], v[110:113], v[50:65]
	v_mfma_f32_32x32x16_bf16 v[34:49], v[178:181], v[110:113], v[34:49]
	s_and_b64 vcc, exec, s[4:5]
	s_cbranch_vccnz .Lfx_exit
	s_add_i32 s14, s14, -1
	v_add_u32_e32 v0, 0xffffff7c, v0
	v_lshl_add_u64 v[216:217], v[216:217], 0, s[84:85]
	s_cmp_le_i32 s14, s73
	s_cselect_b64 s[4:5], -1, 0
	s_add_i32 s100, s14, -1
	s_cmp_le_i32 s14, s73
	s_cselect_b32 s76, s14, s100
	s_lshl_b64 s[16:17], s[76:77], 12
	ds_read2_b32 v[114:115], v0 offset1:1
	ds_read2_b32 v[116:117], v0 offset0:2 offset1:3
	ds_read2_b32 v[118:119], v0 offset0:8 offset1:9
	ds_read2_b32 v[120:121], v0 offset0:10 offset1:11
	ds_read2_b32 v[122:123], v0 offset0:16 offset1:17
	ds_read2_b32 v[124:125], v0 offset0:18 offset1:19
	ds_read2_b32 v[126:127], v0 offset0:24 offset1:25
	ds_read2_b32 v[128:129], v0 offset0:26 offset1:27
	s_waitcnt vmcnt(0)
	global_load_dwordx4 v[190:193], v[216:217], off offset:-2048
	global_load_dwordx4 v[186:189], v[216:217], off offset:-1024
	global_load_dwordx4 v[182:185], v[216:217], off
	global_load_dwordx4 v[178:181], v[216:217], off offset:1024
	v_lshl_add_u64 v[234:235], v[214:215], 0, s[16:17]
	global_load_dwordx4 v[174:177], v[234:235], off
	global_load_dwordx4 v[170:173], v[234:235], off offset:1024
	global_load_dwordx4 v[166:169], v[234:235], off offset:2048
	global_load_dwordx4 v[162:165], v[234:235], off offset:3072
	s_branch .Lfx_itera
